# SSD output and state-update MFMA operand reads hoisted to interval tops into free high VGPRs; duplicate-read removal dropped everywhere (it made SSD outputs differ between launches)
# baseline (speedup 1.0000x reference)
.LBB0_442:
	s_mul_i32 s16, s34, 0x18920
	s_xor_b32 s74, s34, 1
	s_mul_i32 s17, s74, 0x6b00
	s_add_i32 s34, s17, 0
	ds_read_b128 v[224:227], v99 offset:36864
	ds_read_b128 v[228:231], v99 offset:36928
	v_add_u32_e32 v222, s16, v100
	v_add_u32_e32 v223, v222, v107
	ds_read_b128 v[232:235], v223 offset:18432
	ds_read_b128 v[236:239], v223 offset:18496
	ds_read_b64 v[240:241], v109 offset:55296
	v_add_u32_e32 v242, v222, v108
	ds_read_b128 v[244:247], v242 offset:18432
	ds_read_b128 v[248:251], v242 offset:18496
	v_mul_f32_e32 v61, 0x3fb8aa3b, v61
	v_exp_f32_e32 v112, v61
	v_ashrrev_i32_e32 v61, 31, v60
	v_lshlrev_b64 v[60:61], 11, v[60:61]
	v_lshl_add_u64 v[124:125], s[8:9], 0, v[60:61]
	v_add_u32_e32 v60, s16, v100
	v_add_u32_e32 v61, v60, v107
	v_pk_mul_f32 v[26:27], v[112:113], v[26:27] op_sel_hi:[0,1]
	v_pk_mul_f32 v[24:25], v[112:113], v[24:25] op_sel_hi:[0,1]
	v_pk_mul_f32 v[30:31], v[112:113], v[30:31] op_sel_hi:[0,1]
	v_pk_mul_f32 v[28:29], v[112:113], v[28:29] op_sel_hi:[0,1]
	s_waitcnt lgkmcnt(3)
	v_mfma_f32_16x16x32_bf16 v[24:27], v[232:235], v[224:227], v[24:27]
	v_add_u32_e32 v60, v60, v108
	v_mfma_f32_16x16x32_bf16 v[24:27], v[236:239], v[228:231], v[24:27]
	v_add3_u32 v111, s34, v82, v83
	v_add_u32_e32 v128, 0xfc00, v111
	s_waitcnt lgkmcnt(2)
	v_lshlrev_b32_e32 v122, 16, v240
	v_and_b32_e32 v123, 0xffff0000, v240
	v_lshlrev_b32_e32 v120, 16, v241
	v_and_b32_e32 v121, 0xffff0000, v241
	s_nop 0
	v_pk_fma_f32 v[24:25], v[46:47], v[122:123], v[24:25]
	v_pk_fma_f32 v[26:27], v[46:47], v[120:121], v[26:27]
	v_cvt_pk_bf16_f32 v24, v24, v25
	v_cvt_pk_bf16_f32 v25, v26, v27
	v_lshl_add_u64 v[120:121], v[124:125], 0, v[168:169]
	global_store_dwordx2 v[120:121], v[24:25], off offset:512
	s_waitcnt lgkmcnt(0)
	v_mfma_f32_16x16x32_bf16 v[24:27], v[244:247], v[224:227], v[28:31]
	s_nop 2
	v_add_u32_e32 v124, s17, v85
	v_add3_u32 v112, s34, v86, v83
	v_mfma_f32_16x16x32_bf16 v[24:27], v[248:251], v[228:231], v[24:27]
	ds_read_b64 v[28:29], v110 offset:55296
	v_add3_u32 v113, s34, v89, v83
	s_mul_i32 s74, s74, 0x18920
	s_add_i32 s29, s29, 64
	s_cmpk_eq_i32 s31, 0x84
	s_waitcnt lgkmcnt(0)
	v_lshlrev_b32_e32 v30, 16, v28
	v_and_b32_e32 v31, 0xffff0000, v28
	v_lshlrev_b32_e32 v28, 16, v29
	v_and_b32_e32 v29, 0xffff0000, v29
	v_pk_fma_f32 v[24:25], v[46:47], v[30:31], v[24:25]
	v_pk_fma_f32 v[26:27], v[46:47], v[28:29], v[26:27]
	v_cvt_pk_bf16_f32 v24, v24, v25
	v_cvt_pk_bf16_f32 v25, v26, v27
	global_store_dwordx2 v[120:121], v[24:25], off offset:544
	v_add_u32_e32 v122, s17, v198
	v_add_u32_e32 v124, s17, v201
	v_add_u32_e32 v123, s74, v200
	v_mov_b32_e32 v154, 0xbfb8aa3b
	ds_read_b32 v131, v122 offset:128
	ds_read_b32 v133, v122 offset:528
	ds_read_b32 v135, v122 offset:928
	ds_read_b32 v137, v122 offset:1328
	ds_read_b32 v139, v122 offset:1728
	ds_read_b32 v141, v122 offset:2128
	ds_read_b128 v[156:159], v124
	ds_read_b32 v143, v122 offset:256
	ds_read_b32 v145, v122 offset:656
	ds_read_b32 v147, v122 offset:1056
	ds_read_b32 v149, v122 offset:1456
	ds_read_b32 v151, v122 offset:1856
	ds_read_b32 v153, v122 offset:2256
	s_waitcnt lgkmcnt(10)
	v_lshlrev_b32_e32 v130, 16, v131
	v_and_b32_e32 v131, 0xffff0000, v131
	v_lshlrev_b32_e32 v132, 16, v133
	v_and_b32_e32 v133, 0xffff0000, v133
	v_lshlrev_b32_e32 v134, 16, v135
	v_and_b32_e32 v135, 0xffff0000, v135
	s_waitcnt lgkmcnt(7)
	v_lshlrev_b32_e32 v136, 16, v137
	v_and_b32_e32 v137, 0xffff0000, v137
	v_lshlrev_b32_e32 v138, 16, v139
	v_and_b32_e32 v139, 0xffff0000, v139
	v_lshlrev_b32_e32 v140, 16, v141
	v_and_b32_e32 v141, 0xffff0000, v141
	v_pk_mul_f32 v[160:161], v[180:181], v[130:131]
	v_pk_mul_f32 v[162:163], v[180:181], v[132:133]
	v_pk_mul_f32 v[164:165], v[180:181], v[134:135]
	v_pk_mul_f32 v[166:167], v[180:181], v[136:137]
	v_pk_fma_f32 v[160:161], v[182:183], v[132:133], v[160:161]
	v_pk_fma_f32 v[162:163], v[182:183], v[134:135], v[162:163]
	v_pk_fma_f32 v[164:165], v[182:183], v[136:137], v[164:165]
	v_pk_fma_f32 v[166:167], v[182:183], v[138:139], v[166:167]
	v_pk_fma_f32 v[160:161], v[184:185], v[134:135], v[160:161]
	v_pk_fma_f32 v[162:163], v[184:185], v[136:137], v[162:163]
	v_pk_fma_f32 v[164:165], v[184:185], v[138:139], v[164:165]
	v_pk_fma_f32 v[166:167], v[184:185], v[140:141], v[166:167]
	v_pk_add_f32 v[160:161], v[186:187], v[160:161]
	v_pk_add_f32 v[162:163], v[186:187], v[162:163]
	v_pk_add_f32 v[164:165], v[186:187], v[164:165]
	v_pk_add_f32 v[166:167], v[186:187], v[166:167]
	v_pk_mul_f32 v[24:25], v[160:161], v[154:155] op_sel_hi:[1,0]
	v_pk_mul_f32 v[26:27], v[162:163], v[154:155] op_sel_hi:[1,0]
	v_pk_mul_f32 v[28:29], v[164:165], v[154:155] op_sel_hi:[1,0]
	v_pk_mul_f32 v[30:31], v[166:167], v[154:155] op_sel_hi:[1,0]
	v_exp_f32_e32 v24, v24
	v_exp_f32_e32 v26, v26
	v_exp_f32_e32 v28, v28
	v_exp_f32_e32 v30, v30
	v_exp_f32_e32 v25, v25
	v_exp_f32_e32 v27, v27
	v_exp_f32_e32 v29, v29
	v_exp_f32_e32 v31, v31
	v_pk_add_f32 v[24:25], v[24:25], 1.0 op_sel_hi:[1,0]
	v_pk_add_f32 v[26:27], v[26:27], 1.0 op_sel_hi:[1,0]
	v_pk_add_f32 v[28:29], v[28:29], 1.0 op_sel_hi:[1,0]
	v_pk_add_f32 v[30:31], v[30:31], 1.0 op_sel_hi:[1,0]
	v_rcp_f32_e32 v24, v24
	v_rcp_f32_e32 v26, v26
	v_rcp_f32_e32 v28, v28
	v_rcp_f32_e32 v30, v30
	v_rcp_f32_e32 v25, v25
	v_rcp_f32_e32 v27, v27
	v_rcp_f32_e32 v29, v29
	v_rcp_f32_e32 v31, v31
	v_pk_mul_f32 v[160:161], v[160:161], v[24:25]
	v_pk_mul_f32 v[162:163], v[162:163], v[26:27]
	v_pk_mul_f32 v[164:165], v[164:165], v[28:29]
	v_pk_mul_f32 v[166:167], v[166:167], v[30:31]
	v_cvt_pk_bf16_f32 v24, v160, v161
	v_cvt_pk_bf16_f32 v26, v162, v163
	v_cvt_pk_bf16_f32 v28, v164, v165
	v_cvt_pk_bf16_f32 v30, v166, v167
	ds_write_b32 v199, v24 offset:9216
	ds_write_b32 v199, v26 offset:9360
	ds_write_b32 v199, v28 offset:9504
	ds_write_b32 v199, v30 offset:9648
	s_waitcnt lgkmcnt(10)
	v_pk_mul_f32 v[112:113], v[160:161], v[156:157] op_sel_hi:[1,0]
	v_pk_mul_f32 v[114:115], v[162:163], v[156:157] op_sel:[0,1]
	v_pk_mul_f32 v[116:117], v[164:165], v[158:159] op_sel_hi:[1,0]
	v_pk_mul_f32 v[118:119], v[166:167], v[158:159] op_sel:[0,1]
	v_cvt_pk_bf16_f32 v24, v112, v114
	v_cvt_pk_bf16_f32 v25, v116, v118
	v_cvt_pk_bf16_f32 v26, v113, v115
	v_cvt_pk_bf16_f32 v27, v117, v119
	ds_write_b64 v123, v[24:25] offset:27648
	ds_write_b64 v123, v[26:27] offset:27792
	s_waitcnt lgkmcnt(9)
	v_lshlrev_b32_e32 v142, 16, v143
	v_and_b32_e32 v143, 0xffff0000, v143
	v_lshlrev_b32_e32 v144, 16, v145
	v_and_b32_e32 v145, 0xffff0000, v145
	v_lshlrev_b32_e32 v146, 16, v147
	v_and_b32_e32 v147, 0xffff0000, v147
	s_waitcnt lgkmcnt(6)
	v_lshlrev_b32_e32 v148, 16, v149
	v_and_b32_e32 v149, 0xffff0000, v149
	v_lshlrev_b32_e32 v150, 16, v151
	v_and_b32_e32 v151, 0xffff0000, v151
	v_lshlrev_b32_e32 v152, 16, v153
	v_and_b32_e32 v153, 0xffff0000, v153
	v_pk_mul_f32 v[160:161], v[188:189], v[142:143]
	v_pk_mul_f32 v[162:163], v[188:189], v[144:145]
	v_pk_mul_f32 v[164:165], v[188:189], v[146:147]
	v_pk_mul_f32 v[166:167], v[188:189], v[148:149]
	v_pk_fma_f32 v[160:161], v[190:191], v[144:145], v[160:161]
	v_pk_fma_f32 v[162:163], v[190:191], v[146:147], v[162:163]
	v_pk_fma_f32 v[164:165], v[190:191], v[148:149], v[164:165]
	v_pk_fma_f32 v[166:167], v[190:191], v[150:151], v[166:167]
	v_pk_fma_f32 v[160:161], v[192:193], v[146:147], v[160:161]
	v_pk_fma_f32 v[162:163], v[192:193], v[148:149], v[162:163]
	v_pk_fma_f32 v[164:165], v[192:193], v[150:151], v[164:165]
	v_pk_fma_f32 v[166:167], v[192:193], v[152:153], v[166:167]
	v_pk_add_f32 v[160:161], v[194:195], v[160:161]
	v_pk_add_f32 v[162:163], v[194:195], v[162:163]
	v_pk_add_f32 v[164:165], v[194:195], v[164:165]
	v_pk_add_f32 v[166:167], v[194:195], v[166:167]
	v_pk_mul_f32 v[24:25], v[160:161], v[154:155] op_sel_hi:[1,0]
	v_pk_mul_f32 v[26:27], v[162:163], v[154:155] op_sel_hi:[1,0]
	v_pk_mul_f32 v[28:29], v[164:165], v[154:155] op_sel_hi:[1,0]
	v_pk_mul_f32 v[30:31], v[166:167], v[154:155] op_sel_hi:[1,0]
	v_exp_f32_e32 v24, v24
	v_exp_f32_e32 v26, v26
	v_exp_f32_e32 v28, v28
	v_exp_f32_e32 v30, v30
	v_exp_f32_e32 v25, v25
	v_exp_f32_e32 v27, v27
	v_exp_f32_e32 v29, v29
	v_exp_f32_e32 v31, v31
	v_pk_add_f32 v[24:25], v[24:25], 1.0 op_sel_hi:[1,0]
	v_pk_add_f32 v[26:27], v[26:27], 1.0 op_sel_hi:[1,0]
	v_pk_add_f32 v[28:29], v[28:29], 1.0 op_sel_hi:[1,0]
	v_pk_add_f32 v[30:31], v[30:31], 1.0 op_sel_hi:[1,0]
	v_rcp_f32_e32 v24, v24
	v_rcp_f32_e32 v26, v26
	v_rcp_f32_e32 v28, v28
	v_rcp_f32_e32 v30, v30
	v_rcp_f32_e32 v25, v25
	v_rcp_f32_e32 v27, v27
	v_rcp_f32_e32 v29, v29
	v_rcp_f32_e32 v31, v31
	v_pk_mul_f32 v[160:161], v[160:161], v[24:25]
	v_pk_mul_f32 v[162:163], v[162:163], v[26:27]
	v_pk_mul_f32 v[164:165], v[164:165], v[28:29]
	v_pk_mul_f32 v[166:167], v[166:167], v[30:31]
	v_cvt_pk_bf16_f32 v24, v160, v161
	v_cvt_pk_bf16_f32 v26, v162, v163
	v_cvt_pk_bf16_f32 v28, v164, v165
	v_cvt_pk_bf16_f32 v30, v166, v167
	ds_write_b32 v199, v24 offset:0
	ds_write_b32 v199, v26 offset:144
	ds_write_b32 v199, v28 offset:288
	ds_write_b32 v199, v30 offset:432
	s_mov_b32 s35, s31
	v_add_u32_e32 v121, s16, v99
	v_mov_b32_e32 v24, s84
	s_waitcnt lgkmcnt(0)
	s_barrier
	ds_read_b32 v222, v24 offset:252
	ds_read_b128 v[224:227], v121 offset:27648
	ds_read_b128 v[228:231], v61 offset:18432
	ds_read_b128 v[232:235], v121 offset:27712
	ds_read_b128 v[236:239], v61 offset:18496
	ds_read_b128 v[240:243], v121 offset:27648
	ds_read_b128 v[244:247], v60 offset:18432
	ds_read_b128 v[248:251], v121 offset:27712
	s_waitcnt lgkmcnt(7)
	v_mul_f32_e32 v24, 0x3fb8aa3b, v222
	v_exp_f32_e32 v120, v24
	s_nop 0
	v_pk_mul_f32 v[18:19], v[18:19], v[120:121] op_sel_hi:[1,0]
	v_pk_mul_f32 v[16:17], v[16:17], v[120:121] op_sel_hi:[1,0]
	v_pk_mul_f32 v[22:23], v[22:23], v[120:121] op_sel_hi:[1,0]
	v_pk_mul_f32 v[20:21], v[20:21], v[120:121] op_sel_hi:[1,0]
	s_waitcnt lgkmcnt(3)
	v_mfma_f32_16x16x32_bf16 v[16:19], v[224:227], v[228:231], v[16:19]
	v_mfma_f32_16x16x32_bf16 v[16:19], v[232:235], v[236:239], v[16:19]
	v_add_u32_e32 v26, v106, v107
	s_nop 6
	v_cvt_pk_bf16_f32 v24, v16, v17
	v_cvt_pk_bf16_f32 v25, v18, v19
	ds_write_b64 v26, v[24:25] offset:46080
	s_waitcnt lgkmcnt(2)
	v_mfma_f32_16x16x32_bf16 v[20:23], v[240:243], v[244:247], v[20:23]
	ds_read_b128 v[28:31], v60 offset:18496
	s_waitcnt lgkmcnt(0)
	v_mfma_f32_16x16x32_bf16 v[20:23], v[248:251], v[28:31], v[20:23]
	v_add_u32_e32 v26, v106, v108
	s_nop 6
	v_cvt_pk_bf16_f32 v24, v20, v21
	v_cvt_pk_bf16_f32 v25, v22, v23
	ds_write_b64 v26, v[24:25] offset:46080
	v_add_u32_e32 v122, s17, v198
	v_add_u32_e32 v124, s17, v201
	v_add_u32_e32 v124, 0xffffff00, v124
	v_add_u32_e32 v123, s74, v200
	v_mov_b32_e32 v154, 0xbfb8aa3b
	ds_read_b32 v131, v122 offset:0
	ds_read_b32 v133, v122 offset:400
	ds_read_b32 v135, v122 offset:800
	ds_read_b32 v137, v122 offset:1200
	ds_read_b32 v139, v122 offset:1600
	ds_read_b32 v141, v122 offset:2000
	ds_read_b128 v[156:159], v124
	s_waitcnt lgkmcnt(4)
	v_lshlrev_b32_e32 v130, 16, v131
	v_and_b32_e32 v131, 0xffff0000, v131
	v_lshlrev_b32_e32 v132, 16, v133
	v_and_b32_e32 v133, 0xffff0000, v133
	v_lshlrev_b32_e32 v134, 16, v135
	v_and_b32_e32 v135, 0xffff0000, v135
	s_waitcnt lgkmcnt(1)
	v_lshlrev_b32_e32 v136, 16, v137
	v_and_b32_e32 v137, 0xffff0000, v137
	v_lshlrev_b32_e32 v138, 16, v139
	v_and_b32_e32 v139, 0xffff0000, v139
	v_lshlrev_b32_e32 v140, 16, v141
	v_and_b32_e32 v141, 0xffff0000, v141
	v_pk_mul_f32 v[160:161], v[172:173], v[130:131]
	v_pk_mul_f32 v[162:163], v[172:173], v[132:133]
	v_pk_mul_f32 v[164:165], v[172:173], v[134:135]
	v_pk_mul_f32 v[166:167], v[172:173], v[136:137]
	v_pk_fma_f32 v[160:161], v[174:175], v[132:133], v[160:161]
	v_pk_fma_f32 v[162:163], v[174:175], v[134:135], v[162:163]
	v_pk_fma_f32 v[164:165], v[174:175], v[136:137], v[164:165]
	v_pk_fma_f32 v[166:167], v[174:175], v[138:139], v[166:167]
	v_pk_fma_f32 v[160:161], v[176:177], v[134:135], v[160:161]
	v_pk_fma_f32 v[162:163], v[176:177], v[136:137], v[162:163]
	v_pk_fma_f32 v[164:165], v[176:177], v[138:139], v[164:165]
	v_pk_fma_f32 v[166:167], v[176:177], v[140:141], v[166:167]
	v_pk_add_f32 v[160:161], v[178:179], v[160:161]
	v_pk_add_f32 v[162:163], v[178:179], v[162:163]
	v_pk_add_f32 v[164:165], v[178:179], v[164:165]
	v_pk_add_f32 v[166:167], v[178:179], v[166:167]
	v_pk_mul_f32 v[24:25], v[160:161], v[154:155] op_sel_hi:[1,0]
	v_pk_mul_f32 v[26:27], v[162:163], v[154:155] op_sel_hi:[1,0]
	v_pk_mul_f32 v[28:29], v[164:165], v[154:155] op_sel_hi:[1,0]
	v_pk_mul_f32 v[30:31], v[166:167], v[154:155] op_sel_hi:[1,0]
	v_exp_f32_e32 v24, v24
	v_exp_f32_e32 v26, v26
	v_exp_f32_e32 v28, v28
	v_exp_f32_e32 v30, v30
	v_exp_f32_e32 v25, v25
	v_exp_f32_e32 v27, v27
	v_exp_f32_e32 v29, v29
	v_exp_f32_e32 v31, v31
	v_pk_add_f32 v[24:25], v[24:25], 1.0 op_sel_hi:[1,0]
	v_pk_add_f32 v[26:27], v[26:27], 1.0 op_sel_hi:[1,0]
	v_pk_add_f32 v[28:29], v[28:29], 1.0 op_sel_hi:[1,0]
	v_pk_add_f32 v[30:31], v[30:31], 1.0 op_sel_hi:[1,0]
	v_rcp_f32_e32 v24, v24
	v_rcp_f32_e32 v26, v26
	v_rcp_f32_e32 v28, v28
	v_rcp_f32_e32 v30, v30
	v_rcp_f32_e32 v25, v25
	v_rcp_f32_e32 v27, v27
	v_rcp_f32_e32 v29, v29
	v_rcp_f32_e32 v31, v31
	v_pk_mul_f32 v[160:161], v[160:161], v[24:25]
	v_pk_mul_f32 v[162:163], v[162:163], v[26:27]
	v_pk_mul_f32 v[164:165], v[164:165], v[28:29]
	v_pk_mul_f32 v[166:167], v[166:167], v[30:31]
	v_cvt_pk_bf16_f32 v24, v160, v161
	v_cvt_pk_bf16_f32 v26, v162, v163
	v_cvt_pk_bf16_f32 v28, v164, v165
	v_cvt_pk_bf16_f32 v30, v166, v167
	ds_write_b32 v199, v24 offset:55296
	ds_write_b32 v199, v26 offset:55440
	ds_write_b32 v199, v28 offset:55584
	ds_write_b32 v199, v30 offset:55728
	s_waitcnt lgkmcnt(4)
	v_pk_mul_f32 v[112:113], v[160:161], v[156:157] op_sel_hi:[1,0]
	v_pk_mul_f32 v[114:115], v[162:163], v[156:157] op_sel:[0,1]
	v_pk_mul_f32 v[116:117], v[164:165], v[158:159] op_sel_hi:[1,0]
	v_pk_mul_f32 v[118:119], v[166:167], v[158:159] op_sel:[0,1]
	v_cvt_pk_bf16_f32 v24, v112, v114
	v_cvt_pk_bf16_f32 v25, v116, v118
	v_cvt_pk_bf16_f32 v26, v113, v115
	v_cvt_pk_bf16_f32 v27, v117, v119
	ds_write_b64 v123, v[24:25] offset:18432
	ds_write_b64 v123, v[26:27] offset:18576
	s_waitcnt lgkmcnt(0)
	s_barrier
	s_cbranch_scc1 .LBB0_474
